# G4 epilogue stores write-through (sc1) as well
# baseline (speedup 1.0000x reference)
; #define PG8_STAGE(bufoff, gbase, voff) do { const char* _gb = (const char*)(gbase); asm volatile("" : "+s"(_gb)); _Pragma("unroll") for (int _i = 0; _i < 2; ++_i) \
;         __builtin_amdgcn_global_load_lds((const unsigned*)(_gb + (voff)[_i]), (LAS unsigned*)(lds + (bufoff) + ldsw + _i * 8192), 16, 0, 0); } while (0)
; #define PG8_LDA(dst, b, h) do { _Pragma("unroll") for (int m = 0; m < 4; ++m) _Pragma("unroll") for (int k = 0; k < 2; ++k) dst[m][k] = *(const LAS bf16x8*)(lds + PG8_SA(b, h) + aoff + m * 2048 + k * 1024); } while (0)
; #define PG8_LDB(dst, b, h) do { _Pragma("unroll") for (int n = 0; n < 2; ++n) _Pragma("unroll") for (int k = 0; k < 2; ++k) dst[n][k] = *(const LAS bf16x8*)(lds + PG8_SB(b, h) + boff + n * 2048 + k * 1024); } while (0)
; #define PG8_MMA(ai, bj, At, Bt) do { __builtin_amdgcn_s_setprio(1); _Pragma("unroll") for (int m = 0; m < 4; ++m) _Pragma("unroll") for (int n = 0; n < 2; ++n) _Pragma("unroll") for (int k = 0; k < 2; ++k) \
;         acc[ai][bj][m][n] = __builtin_amdgcn_mfma_f32_16x16x32_bf16(Bt[n][k], At[m][k], acc[ai][bj][m][n], 0, 0, 0); __builtin_amdgcn_s_setprio(0); } while (0)
; #define PG8_WAIT_V(n) asm volatile("s_waitcnt vmcnt(" #n ")" ::: "memory")
; #define PG8_WAIT_L(n) asm volatile("s_waitcnt lgkmcnt(" #n ")" ::: "memory")
; #define PG8_BAR __builtin_amdgcn_s_barrier()
; #define PG8_SCHED __builtin_amdgcn_sched_barrier(0)
; template <class Epi, class Sched>
; __device__ __forceinline__ void gemm_phase(LAS unsigned char* lds, const Gemm g, const Sched& S, const Epi& E) {
;     ...
;             PG8_LDB(B0, 0, 0); PG8_SCHED; PG8_LDA(At, 0, 0); PG8_STAGE(PG8_SA(1, 1), a1 + hA, voffA);
;             PG8_WAIT_L(8); PG8_BAR; PG8_WAIT_L(0); PG8_MMA(0, 0, At, B0); PG8_BAR; PG8_SCHED;
;             PG8_LDB(B1, 0, 1); PG8_STAGE(PG8_SB(0, 0), b2, voffB);
;             PG8_BAR; PG8_WAIT_L(0); PG8_MMA(0, 1, At, B1); PG8_BAR;
;             PG8_LDA(At, 0, 1); PG8_STAGE(PG8_SA(0, 0), a2, voffA);
;             PG8_BAR; PG8_WAIT_L(0); PG8_MMA(1, 0, At, B0); PG8_BAR; PG8_SCHED;
;             PG8_STAGE(PG8_SB(0, 1), b2 + hB, voffB);
;             PG8_WAIT_V(6); PG8_BAR; PG8_MMA(1, 1, At, B1); PG8_BAR;
.LBB0_555:
	v_add_u32_e32 v140, s28, v179
	ds_read_b128 v[128:131], v140
	ds_read_b128 v[174:177], v140 offset:1024
	ds_read_b128 v[182:185], v140 offset:2048
	ds_read_b128 v[186:189], v140 offset:3072
	s_add_u32 s14, s12, 0x100
	s_addc_u32 s15, s13, 0
	s_cmp_eq_u32 s43, 12
	s_cselect_b32 s20, s6, s14
	s_cselect_b32 s21, s7, s15
	s_cselect_b32 s16, s40, s41
	s_cselect_b32 s17, s39, s42
	s_add_u32 s18, s20, 0x80
	s_addc_u32 s19, s21, 0
	s_add_u32 s12, s12, 0x40080
	s_addc_u32 s13, s13, 0
	s_mov_b32 m0, s30
	ds_read_b128 v[196:199], v181
	ds_read_b128 v[200:203], v181 offset:1024
	ds_read_b128 v[204:207], v181 offset:2048
	ds_read_b128 v[208:211], v181 offset:3072
	ds_read_b128 v[212:215], v181 offset:4096
	ds_read_b128 v[216:219], v181 offset:5120
	ds_read_b128 v[220:223], v181 offset:6144
	ds_read_b128 v[224:227], v181 offset:7168
	s_nop 0
	v_lshl_add_u64 v[190:191], s[12:13], 0, v[138:139]
	global_load_lds_dwordx4 v[190:191], off
	v_lshl_add_u64 v[190:191], s[12:13], 0, v[134:135]
	s_mov_b32 m0, s31
	s_nop 0
	global_load_lds_dwordx4 v[190:191], off
	s_waitcnt lgkmcnt(8)
	s_barrier
	s_waitcnt lgkmcnt(0)
	s_setprio 1
	s_waitcnt lgkmcnt(0)
	v_mfma_f32_16x16x32_bf16 v[124:127], v[128:131], v[196:199], v[124:127]
	v_mfma_f32_16x16x32_bf16 v[120:123], v[182:185], v[196:199], v[120:123]
	v_mfma_f32_16x16x32_bf16 v[116:119], v[128:131], v[204:207], v[116:119]
	v_mfma_f32_16x16x32_bf16 v[112:115], v[182:185], v[204:207], v[112:115]
	v_mfma_f32_16x16x32_bf16 v[92:95], v[128:131], v[212:215], v[92:95]
	v_mfma_f32_16x16x32_bf16 v[88:91], v[182:185], v[212:215], v[88:91]
	v_mfma_f32_16x16x32_bf16 v[76:79], v[128:131], v[220:223], v[76:79]
	v_mfma_f32_16x16x32_bf16 v[72:75], v[182:185], v[220:223], v[72:75]
	v_mfma_f32_16x16x32_bf16 v[124:127], v[174:177], v[200:203], v[124:127]
	v_mfma_f32_16x16x32_bf16 v[120:123], v[186:189], v[200:203], v[120:123]
	v_mfma_f32_16x16x32_bf16 v[116:119], v[174:177], v[208:211], v[116:119]
	v_mfma_f32_16x16x32_bf16 v[112:115], v[186:189], v[208:211], v[112:115]
	v_mfma_f32_16x16x32_bf16 v[92:95], v[174:177], v[216:219], v[92:95]
	v_mfma_f32_16x16x32_bf16 v[88:91], v[186:189], v[216:219], v[88:91]
	v_mfma_f32_16x16x32_bf16 v[76:79], v[174:177], v[224:227], v[76:79]
	v_mfma_f32_16x16x32_bf16 v[72:75], v[186:189], v[224:227], v[72:75]
	s_setprio 0
	s_barrier
	v_add_u32_e32 v140, s29, v179
	s_mov_b64 s[12:13], s[16:17]
	s_mov_b32 m0, s33
	ds_read_b128 v[228:231], v140
	ds_read_b128 v[232:235], v140 offset:1024
	ds_read_b128 v[236:239], v140 offset:2048
	ds_read_b128 v[240:243], v140 offset:3072
	s_nop 0
	v_lshl_add_u64 v[190:191], s[12:13], 0, v[136:137]
	global_load_lds_dwordx4 v[190:191], off
	v_lshl_add_u64 v[190:191], s[12:13], 0, v[132:133]
	s_mov_b32 m0, s34
	s_nop 0
	global_load_lds_dwordx4 v[190:191], off
	s_barrier
	s_waitcnt lgkmcnt(0)
	s_setprio 1
	s_waitcnt lgkmcnt(0)
	v_mfma_f32_16x16x32_bf16 v[108:111], v[228:231], v[196:199], v[108:111]
	v_mfma_f32_16x16x32_bf16 v[104:107], v[236:239], v[196:199], v[104:107]
	v_mfma_f32_16x16x32_bf16 v[100:103], v[228:231], v[204:207], v[100:103]
	v_mfma_f32_16x16x32_bf16 v[96:99], v[236:239], v[204:207], v[96:99]
	v_mfma_f32_16x16x32_bf16 v[84:87], v[228:231], v[212:215], v[84:87]
	v_mfma_f32_16x16x32_bf16 v[80:83], v[236:239], v[212:215], v[80:83]
	v_mfma_f32_16x16x32_bf16 v[68:71], v[228:231], v[220:223], v[68:71]
	v_mfma_f32_16x16x32_bf16 v[64:67], v[236:239], v[220:223], v[64:67]
	v_mfma_f32_16x16x32_bf16 v[108:111], v[232:235], v[200:203], v[108:111]
	v_mfma_f32_16x16x32_bf16 v[104:107], v[240:243], v[200:203], v[104:107]
	v_mfma_f32_16x16x32_bf16 v[100:103], v[232:235], v[208:211], v[100:103]
	v_mfma_f32_16x16x32_bf16 v[96:99], v[240:243], v[208:211], v[96:99]
	v_mfma_f32_16x16x32_bf16 v[84:87], v[232:235], v[216:219], v[84:87]
	v_mfma_f32_16x16x32_bf16 v[80:83], v[240:243], v[216:219], v[80:83]
	v_mfma_f32_16x16x32_bf16 v[68:71], v[232:235], v[224:227], v[68:71]
	v_mfma_f32_16x16x32_bf16 v[64:67], v[240:243], v[224:227], v[64:67]
	s_setprio 0
	s_mov_b64 s[12:13], s[20:21]
	s_mov_b32 m0, s3
	s_barrier
	ds_read_b128 v[196:199], v181 offset:16384
	ds_read_b128 v[200:203], v181 offset:17408
	ds_read_b128 v[204:207], v181 offset:18432
	ds_read_b128 v[208:211], v181 offset:19456
	ds_read_b128 v[212:215], v181 offset:20480
	ds_read_b128 v[216:219], v181 offset:21504
	ds_read_b128 v[220:223], v181 offset:22528
	ds_read_b128 v[224:227], v181 offset:23552
	s_nop 0
	v_lshl_add_u64 v[190:191], s[12:13], 0, v[138:139]
	global_load_lds_dwordx4 v[190:191], off
	v_lshl_add_u64 v[190:191], s[12:13], 0, v[134:135]
	s_mov_b32 m0, s23
	s_nop 0
	global_load_lds_dwordx4 v[190:191], off
	s_barrier
	s_waitcnt lgkmcnt(0)
	s_setprio 1
	s_waitcnt lgkmcnt(0)
	v_mfma_f32_16x16x32_bf16 v[60:63], v[128:131], v[196:199], v[60:63]
	v_mfma_f32_16x16x32_bf16 v[56:59], v[182:185], v[196:199], v[56:59]
	v_mfma_f32_16x16x32_bf16 v[52:55], v[128:131], v[204:207], v[52:55]
	v_mfma_f32_16x16x32_bf16 v[48:51], v[182:185], v[204:207], v[48:51]
	v_mfma_f32_16x16x32_bf16 v[28:31], v[128:131], v[212:215], v[28:31]
	v_mfma_f32_16x16x32_bf16 v[24:27], v[182:185], v[212:215], v[24:27]
	v_mfma_f32_16x16x32_bf16 v[12:15], v[128:131], v[220:223], v[12:15]
	v_mfma_f32_16x16x32_bf16 v[8:11], v[182:185], v[220:223], v[8:11]
	v_mfma_f32_16x16x32_bf16 v[60:63], v[174:177], v[200:203], v[60:63]
	v_mfma_f32_16x16x32_bf16 v[56:59], v[186:189], v[200:203], v[56:59]
	v_mfma_f32_16x16x32_bf16 v[52:55], v[174:177], v[208:211], v[52:55]
	v_mfma_f32_16x16x32_bf16 v[48:51], v[186:189], v[208:211], v[48:51]
	v_mfma_f32_16x16x32_bf16 v[28:31], v[174:177], v[216:219], v[28:31]
	v_mfma_f32_16x16x32_bf16 v[24:27], v[186:189], v[216:219], v[24:27]
	v_mfma_f32_16x16x32_bf16 v[12:15], v[174:177], v[224:227], v[12:15]
	v_mfma_f32_16x16x32_bf16 v[8:11], v[186:189], v[224:227], v[8:11]
	s_setprio 0
	s_barrier
; #define PG8_STAGE(bufoff, gbase, voff) do { const char* _gb = (const char*)(gbase); asm volatile("" : "+s"(_gb)); _Pragma("unroll") for (int _i = 0; _i < 2; ++_i) \
;         __builtin_amdgcn_global_load_lds((const unsigned*)(_gb + (voff)[_i]), (LAS unsigned*)(lds + (bufoff) + ldsw + _i * 8192), 16, 0, 0); } while (0)
; #define PG8_LDA(dst, b, h) do { _Pragma("unroll") for (int m = 0; m < 4; ++m) _Pragma("unroll") for (int k = 0; k < 2; ++k) dst[m][k] = *(const LAS bf16x8*)(lds + PG8_SA(b, h) + aoff + m * 2048 + k * 1024); } while (0)
; #define PG8_LDB(dst, b, h) do { _Pragma("unroll") for (int n = 0; n < 2; ++n) _Pragma("unroll") for (int k = 0; k < 2; ++k) dst[n][k] = *(const LAS bf16x8*)(lds + PG8_SB(b, h) + boff + n * 2048 + k * 1024); } while (0)
; #define PG8_MMA(ai, bj, At, Bt) do { __builtin_amdgcn_s_setprio(1); _Pragma("unroll") for (int m = 0; m < 4; ++m) _Pragma("unroll") for (int n = 0; n < 2; ++n) _Pragma("unroll") for (int k = 0; k < 2; ++k) \
;         acc[ai][bj][m][n] = __builtin_amdgcn_mfma_f32_16x16x32_bf16(Bt[n][k], At[m][k], acc[ai][bj][m][n], 0, 0, 0); __builtin_amdgcn_s_setprio(0); } while (0)
; #define PG8_WAIT_V(n) asm volatile("s_waitcnt vmcnt(" #n ")" ::: "memory")
; #define PG8_WAIT_L(n) asm volatile("s_waitcnt lgkmcnt(" #n ")" ::: "memory")
; #define PG8_BAR __builtin_amdgcn_s_barrier()
; #define PG8_SCHED __builtin_amdgcn_sched_barrier(0)
; template <class Epi, class Sched>
; __device__ __forceinline__ void gemm_phase(LAS unsigned char* lds, const Gemm g, const Sched& S, const Epi& E) {
;     ...
;             PG8_WAIT_V(6); PG8_BAR; PG8_MMA(1, 1, At, B1); PG8_BAR;
;             PG8_LDB(B0, 1, 0); PG8_SCHED; PG8_LDA(At, 1, 0); PG8_STAGE(PG8_SA(0, 1), a2 + hA, voffA);
;             PG8_WAIT_L(8); PG8_BAR; PG8_WAIT_L(0); PG8_MMA(0, 0, At, B0); PG8_BAR; PG8_SCHED;
;             PG8_LDB(B1, 1, 1); PG8_STAGE(PG8_SB(1, 0), b3, voffB);
;             PG8_BAR; PG8_WAIT_L(0); PG8_MMA(0, 1, At, B1); PG8_BAR;
;             PG8_LDA(At, 1, 1); PG8_STAGE(PG8_SA(1, 0), a3, voffA);
;             PG8_BAR; PG8_WAIT_L(0); PG8_MMA(1, 0, At, B0); PG8_BAR; PG8_SCHED;
	s_add_u32 s12, s16, 0x40000
	s_addc_u32 s13, s17, 0
	s_mov_b32 m0, s35
	s_nop 0
	v_lshl_add_u64 v[128:129], s[12:13], 0, v[136:137]
	global_load_lds_dwordx4 v[128:129], off
	v_lshl_add_u64 v[128:129], s[12:13], 0, v[132:133]
	s_mov_b32 m0, s36
	s_nop 0
	global_load_lds_dwordx4 v[128:129], off
	s_waitcnt vmcnt(6)
	s_barrier
	s_setprio 1
	v_mfma_f32_16x16x32_bf16 v[44:47], v[228:231], v[196:199], v[44:47]
	v_mfma_f32_16x16x32_bf16 v[40:43], v[236:239], v[196:199], v[40:43]
	v_mfma_f32_16x16x32_bf16 v[36:39], v[228:231], v[204:207], v[36:39]
	v_mfma_f32_16x16x32_bf16 v[32:35], v[236:239], v[204:207], v[32:35]
	v_mfma_f32_16x16x32_bf16 v[20:23], v[228:231], v[212:215], v[20:23]
	v_mfma_f32_16x16x32_bf16 v[16:19], v[236:239], v[212:215], v[16:19]
	v_mfma_f32_16x16x32_bf16 v[4:7], v[228:231], v[220:223], v[4:7]
	v_mfma_f32_16x16x32_bf16 v[0:3], v[236:239], v[220:223], v[0:3]
	v_mfma_f32_16x16x32_bf16 v[44:47], v[232:235], v[200:203], v[44:47]
	v_mfma_f32_16x16x32_bf16 v[40:43], v[240:243], v[200:203], v[40:43]
	v_mfma_f32_16x16x32_bf16 v[36:39], v[232:235], v[208:211], v[36:39]
	v_mfma_f32_16x16x32_bf16 v[32:35], v[240:243], v[208:211], v[32:35]
	v_mfma_f32_16x16x32_bf16 v[20:23], v[232:235], v[216:219], v[20:23]
	v_mfma_f32_16x16x32_bf16 v[16:19], v[240:243], v[216:219], v[16:19]
	v_mfma_f32_16x16x32_bf16 v[4:7], v[232:235], v[224:227], v[4:7]
	v_mfma_f32_16x16x32_bf16 v[0:3], v[240:243], v[224:227], v[0:3]
	s_setprio 0
	s_add_i32 s44, 0, 0x18000
	v_add_u32_e32 v140, s44, v179
	s_barrier
	ds_read_b128 v[128:131], v140
	ds_read_b128 v[174:177], v140 offset:1024
	ds_read_b128 v[182:185], v140 offset:2048
	ds_read_b128 v[186:189], v140 offset:3072
	s_add_u32 s12, s20, 0x40000
	s_addc_u32 s13, s21, 0
	s_mov_b32 m0, s24
	ds_read_b128 v[196:199], v181 offset:32768
	ds_read_b128 v[200:203], v181 offset:33792
	ds_read_b128 v[204:207], v181 offset:34816
	ds_read_b128 v[208:211], v181 offset:35840
	ds_read_b128 v[212:215], v181 offset:36864
	ds_read_b128 v[216:219], v181 offset:37888
	ds_read_b128 v[220:223], v181 offset:38912
	ds_read_b128 v[224:227], v181 offset:39936
	s_nop 0
	v_lshl_add_u64 v[190:191], s[12:13], 0, v[138:139]
	global_load_lds_dwordx4 v[190:191], off
	v_lshl_add_u64 v[190:191], s[12:13], 0, v[134:135]
	s_mov_b32 m0, s25
	s_nop 0
	global_load_lds_dwordx4 v[190:191], off
	s_waitcnt lgkmcnt(8)
	s_barrier
	s_waitcnt lgkmcnt(0)
	s_setprio 1
	s_waitcnt lgkmcnt(0)
	v_mfma_f32_16x16x32_bf16 v[124:127], v[128:131], v[196:199], v[124:127]
	v_mfma_f32_16x16x32_bf16 v[120:123], v[182:185], v[196:199], v[120:123]
	v_mfma_f32_16x16x32_bf16 v[116:119], v[128:131], v[204:207], v[116:119]
	v_mfma_f32_16x16x32_bf16 v[112:115], v[182:185], v[204:207], v[112:115]
	v_mfma_f32_16x16x32_bf16 v[92:95], v[128:131], v[212:215], v[92:95]
	v_mfma_f32_16x16x32_bf16 v[88:91], v[182:185], v[212:215], v[88:91]
	v_mfma_f32_16x16x32_bf16 v[76:79], v[128:131], v[220:223], v[76:79]
	v_mfma_f32_16x16x32_bf16 v[72:75], v[182:185], v[220:223], v[72:75]
	v_mfma_f32_16x16x32_bf16 v[124:127], v[174:177], v[200:203], v[124:127]
	v_mfma_f32_16x16x32_bf16 v[120:123], v[186:189], v[200:203], v[120:123]
	v_mfma_f32_16x16x32_bf16 v[116:119], v[174:177], v[208:211], v[116:119]
	v_mfma_f32_16x16x32_bf16 v[112:115], v[186:189], v[208:211], v[112:115]
	v_mfma_f32_16x16x32_bf16 v[92:95], v[174:177], v[216:219], v[92:95]
	v_mfma_f32_16x16x32_bf16 v[88:91], v[186:189], v[216:219], v[88:91]
	v_mfma_f32_16x16x32_bf16 v[76:79], v[174:177], v[224:227], v[76:79]
	v_mfma_f32_16x16x32_bf16 v[72:75], v[186:189], v[224:227], v[72:75]
	s_setprio 0
	s_barrier
	s_add_i32 s20, 0, 0x1c000
	s_add_u32 s12, s16, 0x80
	v_add_u32_e32 v140, s20, v179
	s_addc_u32 s13, s17, 0
	s_add_i32 s21, s44, s22
	ds_read_b128 v[228:231], v140
	ds_read_b128 v[232:235], v140 offset:1024
	ds_read_b128 v[236:239], v140 offset:2048
	ds_read_b128 v[240:243], v140 offset:3072
	s_mov_b32 m0, s21
	v_lshl_add_u64 v[190:191], s[12:13], 0, v[136:137]
	global_load_lds_dwordx4 v[190:191], off
	v_lshl_add_u64 v[190:191], s[12:13], 0, v[132:133]
	s_add_i32 m0, s21, 0x2000
	s_nop 0
	global_load_lds_dwordx4 v[190:191], off
	s_barrier
	s_waitcnt lgkmcnt(0)
	s_setprio 1
	s_waitcnt lgkmcnt(0)
	v_mfma_f32_16x16x32_bf16 v[108:111], v[228:231], v[196:199], v[108:111]
	v_mfma_f32_16x16x32_bf16 v[104:107], v[236:239], v[196:199], v[104:107]
	v_mfma_f32_16x16x32_bf16 v[100:103], v[228:231], v[204:207], v[100:103]
	v_mfma_f32_16x16x32_bf16 v[96:99], v[236:239], v[204:207], v[96:99]
	v_mfma_f32_16x16x32_bf16 v[84:87], v[228:231], v[212:215], v[84:87]
	v_mfma_f32_16x16x32_bf16 v[80:83], v[236:239], v[212:215], v[80:83]
	v_mfma_f32_16x16x32_bf16 v[68:71], v[228:231], v[220:223], v[68:71]
	v_mfma_f32_16x16x32_bf16 v[64:67], v[236:239], v[220:223], v[64:67]
	v_mfma_f32_16x16x32_bf16 v[108:111], v[232:235], v[200:203], v[108:111]
	v_mfma_f32_16x16x32_bf16 v[104:107], v[240:243], v[200:203], v[104:107]
	v_mfma_f32_16x16x32_bf16 v[100:103], v[232:235], v[208:211], v[100:103]
	v_mfma_f32_16x16x32_bf16 v[96:99], v[240:243], v[208:211], v[96:99]
	v_mfma_f32_16x16x32_bf16 v[84:87], v[232:235], v[216:219], v[84:87]
	v_mfma_f32_16x16x32_bf16 v[80:83], v[240:243], v[216:219], v[80:83]
	v_mfma_f32_16x16x32_bf16 v[68:71], v[232:235], v[224:227], v[68:71]
	v_mfma_f32_16x16x32_bf16 v[64:67], v[240:243], v[224:227], v[64:67]
	s_setprio 0
	s_mov_b32 m0, s26
	s_barrier
	ds_read_b128 v[196:199], v181 offset:49152
	ds_read_b128 v[200:203], v181 offset:50176
	ds_read_b128 v[204:207], v181 offset:51200
	ds_read_b128 v[208:211], v181 offset:52224
	ds_read_b128 v[212:215], v181 offset:53248
	ds_read_b128 v[216:219], v181 offset:54272
	ds_read_b128 v[220:223], v181 offset:55296
	ds_read_b128 v[224:227], v181 offset:56320
	s_nop 0
	v_lshl_add_u64 v[190:191], s[18:19], 0, v[138:139]
	global_load_lds_dwordx4 v[190:191], off
	v_lshl_add_u64 v[190:191], s[18:19], 0, v[134:135]
	s_mov_b32 m0, s27
	s_nop 0
	global_load_lds_dwordx4 v[190:191], off
	s_barrier
; __device__ __forceinline__ float bflo(unsigned w) { return __uint_as_float(w << 16); }
; __device__ __forceinline__ float bfhi(unsigned w) { return __uint_as_float(w & 0xffff0000u); }
; #define PG8_STAGE(bufoff, gbase, voff) do { const char* _gb = (const char*)(gbase); asm volatile("" : "+s"(_gb)); _Pragma("unroll") for (int _i = 0; _i < 2; ++_i) \
;         __builtin_amdgcn_global_load_lds((const unsigned*)(_gb + (voff)[_i]), (LAS unsigned*)(lds + (bufoff) + ldsw + _i * 8192), 16, 0, 0); } while (0)
; #define PG8_MMA(ai, bj, At, Bt) do { __builtin_amdgcn_s_setprio(1); _Pragma("unroll") for (int m = 0; m < 4; ++m) _Pragma("unroll") for (int n = 0; n < 2; ++n) _Pragma("unroll") for (int k = 0; k < 2; ++k) \
;         acc[ai][bj][m][n] = __builtin_amdgcn_mfma_f32_16x16x32_bf16(Bt[n][k], At[m][k], acc[ai][bj][m][n], 0, 0, 0); __builtin_amdgcn_s_setprio(0); } while (0)
; #define PG8_BAR __builtin_amdgcn_s_barrier()
; template <class Epi, class Sched>
; __device__ __forceinline__ void gemm_phase(LAS unsigned char* lds, const Gemm g, const Sched& S, const Epi& E) {
;     ...
;             PG8_BAR; PG8_WAIT_L(0); PG8_MMA(1, 0, At, B0); PG8_BAR; PG8_SCHED;
;             PG8_STAGE(PG8_SB(1, 1), b3 + hB, voffB);
;             PG8_WAIT_V(6); PG8_BAR; PG8_MMA(1, 1, At, B1); PG8_BAR;
;         }
;     __device__ __forceinline__ void operator()(const f32x4 (&acc)[2][2][4][2], const Unit& u, int wr, int wc, int fr, int fq) const {
;         const int row0 = u.pm * BM + wr * 64 + fr, col0 = u.pn * BM + wc * 32 + 8 * fq;
; #pragma unroll
;         for (int ai = 0; ai < 2; ++ai) {
;             u32x4 res[4][2];
;             if (RES_BF16) {
; #pragma unroll
;                 for (int m = 0; m < 4; ++m)
; #pragma unroll
;                     for (int bj = 0; bj < 2; ++bj) res[m][bj] = *(const u32x4*)(xb + (size_t)(row0 + ai * HALF + m * 16) * 1024 + col0 + bj * HALF);
;             }
; #pragma unroll
;             for (int m = 0; m < 4; ++m) { const int row = row0 + ai * HALF + m * 16; bf16_t* yp = Y + (size_t)row * LDP + col0;
; #pragma unroll
;                 for (int bj = 0; bj < 2; ++bj) { f32x4 v0 = acc[ai][bj][m][0], v1 = acc[ai][bj][m][1];
;                     if (RES_BF16) { const u32x4 w = res[m][bj];
;                         v0 += (f32x4){bflo(w.x), bfhi(w.x), bflo(w.y), bfhi(w.y)} * ALPHA; v1 += (f32x4){bflo(w.z), bfhi(w.z), bflo(w.w), bfhi(w.w)} * ALPHA; }
	s_waitcnt lgkmcnt(0)
	s_setprio 1
	s_waitcnt lgkmcnt(0)
	v_mfma_f32_16x16x32_bf16 v[60:63], v[128:131], v[196:199], v[60:63]
	v_mfma_f32_16x16x32_bf16 v[56:59], v[182:185], v[196:199], v[56:59]
	v_mfma_f32_16x16x32_bf16 v[52:55], v[128:131], v[204:207], v[52:55]
	v_mfma_f32_16x16x32_bf16 v[48:51], v[182:185], v[204:207], v[48:51]
	v_mfma_f32_16x16x32_bf16 v[28:31], v[128:131], v[212:215], v[28:31]
	v_mfma_f32_16x16x32_bf16 v[24:27], v[182:185], v[212:215], v[24:27]
	v_mfma_f32_16x16x32_bf16 v[12:15], v[128:131], v[220:223], v[12:15]
	v_mfma_f32_16x16x32_bf16 v[8:11], v[182:185], v[220:223], v[8:11]
	v_mfma_f32_16x16x32_bf16 v[60:63], v[174:177], v[200:203], v[60:63]
	v_mfma_f32_16x16x32_bf16 v[56:59], v[186:189], v[200:203], v[56:59]
	v_mfma_f32_16x16x32_bf16 v[52:55], v[174:177], v[208:211], v[52:55]
	v_mfma_f32_16x16x32_bf16 v[48:51], v[186:189], v[208:211], v[48:51]
	v_mfma_f32_16x16x32_bf16 v[28:31], v[174:177], v[216:219], v[28:31]
	v_mfma_f32_16x16x32_bf16 v[24:27], v[186:189], v[216:219], v[24:27]
	v_mfma_f32_16x16x32_bf16 v[12:15], v[174:177], v[224:227], v[12:15]
	v_mfma_f32_16x16x32_bf16 v[8:11], v[186:189], v[224:227], v[8:11]
	s_setprio 0
	s_barrier
	s_add_u32 s12, s16, 0x40080
	s_addc_u32 s13, s17, 0
	s_add_i32 s16, s20, s22
	s_mov_b32 m0, s16
	v_lshl_add_u64 v[128:129], s[12:13], 0, v[136:137]
	global_load_lds_dwordx4 v[128:129], off
	v_lshl_add_u64 v[128:129], s[12:13], 0, v[132:133]
	s_add_i32 m0, s16, 0x2000
	s_nop 0
	global_load_lds_dwordx4 v[128:129], off
	s_waitcnt vmcnt(6)
	s_barrier
	s_setprio 1
	v_mfma_f32_16x16x32_bf16 v[44:47], v[228:231], v[196:199], v[44:47]
	v_mfma_f32_16x16x32_bf16 v[40:43], v[236:239], v[196:199], v[40:43]
	v_mfma_f32_16x16x32_bf16 v[36:39], v[228:231], v[204:207], v[36:39]
	v_mfma_f32_16x16x32_bf16 v[32:35], v[236:239], v[204:207], v[32:35]
	v_mfma_f32_16x16x32_bf16 v[20:23], v[228:231], v[212:215], v[20:23]
	v_mfma_f32_16x16x32_bf16 v[16:19], v[236:239], v[212:215], v[16:19]
	v_mfma_f32_16x16x32_bf16 v[4:7], v[228:231], v[220:223], v[4:7]
	v_mfma_f32_16x16x32_bf16 v[0:3], v[236:239], v[220:223], v[0:3]
	v_mfma_f32_16x16x32_bf16 v[44:47], v[232:235], v[200:203], v[44:47]
	v_mfma_f32_16x16x32_bf16 v[40:43], v[240:243], v[200:203], v[40:43]
	v_mfma_f32_16x16x32_bf16 v[36:39], v[232:235], v[208:211], v[36:39]
	v_mfma_f32_16x16x32_bf16 v[32:35], v[240:243], v[208:211], v[32:35]
	v_mfma_f32_16x16x32_bf16 v[20:23], v[232:235], v[216:219], v[20:23]
	v_mfma_f32_16x16x32_bf16 v[16:19], v[240:243], v[216:219], v[16:19]
	v_mfma_f32_16x16x32_bf16 v[4:7], v[232:235], v[224:227], v[4:7]
	v_mfma_f32_16x16x32_bf16 v[0:3], v[240:243], v[224:227], v[0:3]
	s_setprio 0
	s_add_i32 s43, s43, 2
	s_add_u32 s41, s41, 0x100
	s_addc_u32 s42, s42, 0
	s_cmp_gt_u32 s43, 13
	s_mov_b64 s[12:13], s[14:15]
	s_barrier
	s_cbranch_scc0 .LBB0_555
	v_lshl_or_b32 v140, s38, 8, v180
	v_lshlrev_b64 v[174:175], 1, v[140:141]
	v_lshl_add_u64 v[176:177], s[76:77], 0, v[174:175]
	v_lshl_add_u64 v[128:129], v[176:177], 0, v[142:143]
	global_load_dwordx4 v[182:185], v[128:129], off
	global_load_dwordx4 v[186:189], v[128:129], off offset:256
	v_lshl_add_u64 v[128:129], v[176:177], 0, v[144:145]
	v_lshl_add_u64 v[190:191], v[176:177], 0, v[146:147]
	global_load_dwordx4 v[196:199], v[128:129], off
	global_load_dwordx4 v[200:203], v[128:129], off offset:256
	v_lshl_add_u64 v[212:213], v[176:177], 0, v[148:149]
	global_load_dwordx4 v[128:131], v[190:191], off
	global_load_dwordx4 v[204:207], v[190:191], off offset:256
	global_load_dwordx4 v[208:211], v[212:213], off
	s_nop 0
	global_load_dwordx4 v[212:215], v[212:213], off offset:256
	v_lshl_add_u64 v[216:217], v[150:151], 0, v[174:175]
	v_lshl_add_u64 v[218:219], v[152:153], 0, v[174:175]
	v_lshl_add_u64 v[220:221], v[154:155], 0, v[174:175]
	s_waitcnt vmcnt(0)
	v_lshlrev_b32_e32 v190, 16, v182
	v_and_b32_e32 v191, 0xffff0000, v182
	v_lshlrev_b32_e32 v182, 16, v183
	v_and_b32_e32 v183, 0xffff0000, v183
	v_lshlrev_b32_e32 v222, 16, v184
	v_and_b32_e32 v223, 0xffff0000, v184
	v_lshlrev_b32_e32 v184, 16, v185
	v_and_b32_e32 v185, 0xffff0000, v185
	v_lshlrev_b32_e32 v234, 16, v202
	v_and_b32_e32 v235, 0xffff0000, v202
	v_lshlrev_b32_e32 v236, 16, v128
	v_and_b32_e32 v237, 0xffff0000, v128
	v_lshlrev_b32_e32 v128, 16, v129
	v_and_b32_e32 v129, 0xffff0000, v129
	v_lshlrev_b32_e32 v224, 16, v186
	v_and_b32_e32 v225, 0xffff0000, v186
	v_lshlrev_b32_e32 v186, 16, v187
	v_and_b32_e32 v187, 0xffff0000, v187
	v_lshlrev_b32_e32 v226, 16, v188
	v_and_b32_e32 v227, 0xffff0000, v188
	v_lshlrev_b32_e32 v188, 16, v189
	v_and_b32_e32 v189, 0xffff0000, v189
	v_pk_fma_f32 v[126:127], v[182:183], s[8:9], v[126:127] op_sel_hi:[1,0,1]
	v_pk_fma_f32 v[124:125], v[190:191], s[8:9], v[124:125] op_sel_hi:[1,0,1]
	v_pk_fma_f32 v[122:123], v[184:185], s[8:9], v[122:123] op_sel_hi:[1,0,1]
	v_pk_fma_f32 v[120:121], v[222:223], s[8:9], v[120:121] op_sel_hi:[1,0,1]
	v_pk_fma_f32 v[182:183], v[234:235], s[8:9], v[96:97] op_sel_hi:[1,0,1]
	v_pk_fma_f32 v[128:129], v[128:129], s[8:9], v[94:95] op_sel_hi:[1,0,1]
	v_cvt_pk_bf16_f32 v94, v124, v125
	v_cvt_pk_bf16_f32 v95, v126, v127
	v_cvt_pk_bf16_f32 v96, v120, v121
	v_cvt_pk_bf16_f32 v97, v122, v123
	v_lshlrev_b32_e32 v228, 16, v196
	v_and_b32_e32 v229, 0xffff0000, v196
	v_lshlrev_b32_e32 v196, 16, v197
	v_and_b32_e32 v197, 0xffff0000, v197
	v_lshlrev_b32_e32 v230, 16, v198
	v_and_b32_e32 v231, 0xffff0000, v198
	v_lshlrev_b32_e32 v198, 16, v199
	v_and_b32_e32 v199, 0xffff0000, v199
	v_pk_fma_f32 v[110:111], v[186:187], s[8:9], v[110:111] op_sel_hi:[1,0,1]
	v_pk_fma_f32 v[108:109], v[224:225], s[8:9], v[108:109] op_sel_hi:[1,0,1]
	v_pk_fma_f32 v[106:107], v[188:189], s[8:9], v[106:107] op_sel_hi:[1,0,1]
; __device__ __forceinline__ unsigned cvt_pk(float lo, float hi) { unsigned r; asm volatile("v_cvt_pk_bf16_f32 %0, %1, %2" : "=v"(r) : "v"(lo), "v"(hi)); return r; }
; __device__ __forceinline__ float bflo(unsigned w) { return __uint_as_float(w << 16); }
; __device__ __forceinline__ float bfhi(unsigned w) { return __uint_as_float(w & 0xffff0000u); }
;     __device__ __forceinline__ void operator()(const f32x4 (&acc)[2][2][4][2], const Unit& u, int wr, int wc, int fr, int fq) const {
;     ...
;         for (int ai = 0; ai < 2; ++ai) {
;             u32x4 res[4][2];
;             if (RES_BF16) {
; #pragma unroll
;                 for (int m = 0; m < 4; ++m)
; #pragma unroll
;                     for (int bj = 0; bj < 2; ++bj) res[m][bj] = *(const u32x4*)(xb + (size_t)(row0 + ai * HALF + m * 16) * 1024 + col0 + bj * HALF);
;             }
; #pragma unroll
;             for (int m = 0; m < 4; ++m) { const int row = row0 + ai * HALF + m * 16; bf16_t* yp = Y + (size_t)row * LDP + col0;
; #pragma unroll
;                 for (int bj = 0; bj < 2; ++bj) { f32x4 v0 = acc[ai][bj][m][0], v1 = acc[ai][bj][m][1];
;                     if (RES_BF16) { const u32x4 w = res[m][bj];
;                         v0 += (f32x4){bflo(w.x), bfhi(w.x), bflo(w.y), bfhi(w.y)} * ALPHA; v1 += (f32x4){bflo(w.z), bfhi(w.z), bflo(w.w), bfhi(w.w)} * ALPHA; }
;                     u32x4 o; o.x = cvt_pk(v0[0], v0[1]); o.y = cvt_pk(v0[2], v0[3]); o.z = cvt_pk(v1[0], v1[1]); o.w = cvt_pk(v1[2], v1[3]);
;                     *(u32x4*)(yp + bj * HALF) = o; } }
;             __builtin_amdgcn_sched_barrier(0);
	v_pk_fma_f32 v[104:105], v[226:227], s[8:9], v[104:105] op_sel_hi:[1,0,1]
	global_store_dwordx4 v[216:217], v[94:97], off sc1
	v_lshlrev_b32_e32 v232, 16, v200
	v_and_b32_e32 v233, 0xffff0000, v200
	v_cvt_pk_bf16_f32 v94, v108, v109
	v_cvt_pk_bf16_f32 v95, v110, v111
	v_cvt_pk_bf16_f32 v96, v104, v105
	v_cvt_pk_bf16_f32 v97, v106, v107
	v_lshlrev_b32_e32 v200, 16, v201
	v_and_b32_e32 v201, 0xffff0000, v201
	v_lshlrev_b32_e32 v202, 16, v203
	v_and_b32_e32 v203, 0xffff0000, v203
	v_pk_fma_f32 v[118:119], v[196:197], s[8:9], v[118:119] op_sel_hi:[1,0,1]
	v_pk_fma_f32 v[116:117], v[228:229], s[8:9], v[116:117] op_sel_hi:[1,0,1]
	v_pk_fma_f32 v[114:115], v[198:199], s[8:9], v[114:115] op_sel_hi:[1,0,1]
	v_pk_fma_f32 v[112:113], v[230:231], s[8:9], v[112:113] op_sel_hi:[1,0,1]
	global_store_dwordx4 v[216:217], v[94:97], off offset:256 sc1
	v_pk_fma_f32 v[102:103], v[200:201], s[8:9], v[102:103] op_sel_hi:[1,0,1]
	v_pk_fma_f32 v[100:101], v[232:233], s[8:9], v[100:101] op_sel_hi:[1,0,1]
	v_cvt_pk_bf16_f32 v94, v116, v117
	v_cvt_pk_bf16_f32 v95, v118, v119
	v_cvt_pk_bf16_f32 v96, v112, v113
	v_cvt_pk_bf16_f32 v97, v114, v115
	v_pk_fma_f32 v[98:99], v[202:203], s[8:9], v[98:99] op_sel_hi:[1,0,1]
	global_store_dwordx4 v[218:219], v[94:97], off sc1
	v_pk_fma_f32 v[92:93], v[236:237], s[8:9], v[92:93] op_sel_hi:[1,0,1]
	s_nop 0
	v_cvt_pk_bf16_f32 v94, v100, v101
	v_cvt_pk_bf16_f32 v95, v102, v103
	v_cvt_pk_bf16_f32 v96, v182, v183
	v_cvt_pk_bf16_f32 v97, v98, v99
	global_store_dwordx4 v[218:219], v[94:97], off offset:256 sc1
	s_nop 1
	v_lshlrev_b32_e32 v94, 16, v130
	v_and_b32_e32 v95, 0xffff0000, v130
	v_lshlrev_b32_e32 v96, 16, v131
	v_and_b32_e32 v97, 0xffff0000, v131
	v_pk_fma_f32 v[96:97], v[96:97], s[8:9], v[90:91] op_sel_hi:[1,0,1]
	v_pk_fma_f32 v[90:91], v[94:95], s[8:9], v[88:89] op_sel_hi:[1,0,1]
	v_cvt_pk_bf16_f32 v88, v92, v93
	v_cvt_pk_bf16_f32 v89, v128, v129
	s_nop 0
	v_cvt_pk_bf16_f32 v90, v90, v91
	v_cvt_pk_bf16_f32 v91, v96, v97
	global_store_dwordx4 v[220:221], v[88:91], off sc1
	s_nop 1
	v_lshlrev_b32_e32 v88, 16, v204
	v_and_b32_e32 v89, 0xffff0000, v204
	v_lshlrev_b32_e32 v90, 16, v205
	v_and_b32_e32 v91, 0xffff0000, v205
	v_pk_fma_f32 v[86:87], v[90:91], s[8:9], v[86:87] op_sel_hi:[1,0,1]
	v_pk_fma_f32 v[84:85], v[88:89], s[8:9], v[84:85] op_sel_hi:[1,0,1]
	v_lshlrev_b32_e32 v88, 16, v206
	v_and_b32_e32 v89, 0xffff0000, v206
	v_lshlrev_b32_e32 v90, 16, v207
	v_and_b32_e32 v91, 0xffff0000, v207
	v_pk_fma_f32 v[90:91], v[90:91], s[8:9], v[82:83] op_sel_hi:[1,0,1]
	v_pk_fma_f32 v[82:83], v[88:89], s[8:9], v[80:81] op_sel_hi:[1,0,1]
	v_cvt_pk_bf16_f32 v80, v84, v85
	v_cvt_pk_bf16_f32 v81, v86, v87
	v_lshlrev_b32_e32 v84, 16, v209
	v_cvt_pk_bf16_f32 v82, v82, v83
	v_cvt_pk_bf16_f32 v83, v90, v91
	global_store_dwordx4 v[220:221], v[80:83], off offset:256 sc1
	v_and_b32_e32 v85, 0xffff0000, v209
	v_pk_fma_f32 v[78:79], v[84:85], s[8:9], v[78:79] op_sel_hi:[1,0,1]
	v_lshlrev_b32_e32 v82, 16, v208
	v_and_b32_e32 v83, 0xffff0000, v208
	v_pk_fma_f32 v[76:77], v[82:83], s[8:9], v[76:77] op_sel_hi:[1,0,1]
	v_lshlrev_b32_e32 v82, 16, v210
	v_and_b32_e32 v83, 0xffff0000, v210
	v_lshlrev_b32_e32 v84, 16, v211
	v_and_b32_e32 v85, 0xffff0000, v211
	v_pk_fma_f32 v[84:85], v[84:85], s[8:9], v[74:75] op_sel_hi:[1,0,1]
	v_pk_fma_f32 v[74:75], v[82:83], s[8:9], v[72:73] op_sel_hi:[1,0,1]
	v_lshl_add_u64 v[80:81], v[156:157], 0, v[174:175]
	v_cvt_pk_bf16_f32 v72, v76, v77
	v_cvt_pk_bf16_f32 v73, v78, v79
	v_cvt_pk_bf16_f32 v74, v74, v75
	v_cvt_pk_bf16_f32 v75, v84, v85
	global_store_dwordx4 v[80:81], v[72:75], off sc1
	s_nop 1
	v_lshlrev_b32_e32 v72, 16, v212
	v_and_b32_e32 v73, 0xffff0000, v212
	v_lshlrev_b32_e32 v74, 16, v213
	v_and_b32_e32 v75, 0xffff0000, v213
	v_pk_fma_f32 v[70:71], v[74:75], s[8:9], v[70:71] op_sel_hi:[1,0,1]
	v_pk_fma_f32 v[68:69], v[72:73], s[8:9], v[68:69] op_sel_hi:[1,0,1]
	v_lshlrev_b32_e32 v72, 16, v214
	v_and_b32_e32 v73, 0xffff0000, v214
	v_lshlrev_b32_e32 v74, 16, v215
	v_and_b32_e32 v75, 0xffff0000, v215
	v_pk_fma_f32 v[74:75], v[74:75], s[8:9], v[66:67] op_sel_hi:[1,0,1]
	v_pk_fma_f32 v[66:67], v[72:73], s[8:9], v[64:65] op_sel_hi:[1,0,1]
	v_cvt_pk_bf16_f32 v64, v68, v69
	v_cvt_pk_bf16_f32 v65, v70, v71
	s_nop 0
	v_cvt_pk_bf16_f32 v66, v66, v67
	v_cvt_pk_bf16_f32 v67, v74, v75
	global_store_dwordx4 v[80:81], v[64:67], off offset:256 sc1
	s_nop 1
	v_lshl_add_u64 v[64:65], v[176:177], 0, v[158:159]
	global_load_dwordx4 v[68:71], v[64:65], off
	global_load_dwordx4 v[72:75], v[64:65], off offset:256
	v_lshl_add_u64 v[64:65], v[176:177], 0, v[160:161]
	v_lshl_add_u64 v[84:85], v[176:177], 0, v[162:163]
	global_load_dwordx4 v[76:79], v[64:65], off
	global_load_dwordx4 v[80:83], v[64:65], off offset:256
	v_lshl_add_u64 v[92:93], v[176:177], 0, v[164:165]
	global_load_dwordx4 v[64:67], v[84:85], off
	s_nop 0
	global_load_dwordx4 v[84:87], v[84:85], off offset:256
	s_nop 0
	global_load_dwordx4 v[88:91], v[92:93], off
	s_nop 0
	global_load_dwordx4 v[92:95], v[92:93], off offset:256
	v_lshl_add_u64 v[96:97], v[166:167], 0, v[174:175]
	v_lshl_add_u64 v[98:99], v[168:169], 0, v[174:175]
	v_lshl_add_u64 v[100:101], v[170:171], 0, v[174:175]
	s_waitcnt vmcnt(0)
; __device__ __forceinline__ unsigned cvt_pk(float lo, float hi) { unsigned r; asm volatile("v_cvt_pk_bf16_f32 %0, %1, %2" : "=v"(r) : "v"(lo), "v"(hi)); return r; }
; __device__ __forceinline__ float bflo(unsigned w) { return __uint_as_float(w << 16); }
; __device__ __forceinline__ float bfhi(unsigned w) { return __uint_as_float(w & 0xffff0000u); }
; #define PG8_WAIT_V(n) asm volatile("s_waitcnt vmcnt(" #n ")" ::: "memory")
; #define PG8_BAR __builtin_amdgcn_s_barrier()
; template <class Epi, class Sched>
; __device__ __forceinline__ void gemm_phase(LAS unsigned char* lds, const Gemm g, const Sched& S, const Epi& E) {
;     ...
;         cur = nxt; cA = nA; cB = nB; ++ui;
;     }
;     PG8_WAIT_V(0);
;     if (wr == 0) PG8_BAR;
;     PG8_BAR;
;     __device__ __forceinline__ void operator()(const f32x4 (&acc)[2][2][4][2], const Unit& u, int wr, int wc, int fr, int fq) const {
;     ...
;         for (int ai = 0; ai < 2; ++ai) {
;             u32x4 res[4][2];
;             if (RES_BF16) {
; #pragma unroll
;                 for (int m = 0; m < 4; ++m)
; #pragma unroll
;                     for (int bj = 0; bj < 2; ++bj) res[m][bj] = *(const u32x4*)(xb + (size_t)(row0 + ai * HALF + m * 16) * 1024 + col0 + bj * HALF);
;             }
; #pragma unroll
;             for (int m = 0; m < 4; ++m) { const int row = row0 + ai * HALF + m * 16; bf16_t* yp = Y + (size_t)row * LDP + col0;
; #pragma unroll
;                 for (int bj = 0; bj < 2; ++bj) { f32x4 v0 = acc[ai][bj][m][0], v1 = acc[ai][bj][m][1];
;                     if (RES_BF16) { const u32x4 w = res[m][bj];
;                         v0 += (f32x4){bflo(w.x), bfhi(w.x), bflo(w.y), bfhi(w.y)} * ALPHA; v1 += (f32x4){bflo(w.z), bfhi(w.z), bflo(w.w), bfhi(w.w)} * ALPHA; }
;                     u32x4 o; o.x = cvt_pk(v0[0], v0[1]); o.y = cvt_pk(v0[2], v0[3]); o.z = cvt_pk(v1[0], v1[1]); o.w = cvt_pk(v1[2], v1[3]);
;                     *(u32x4*)(yp + bj * HALF) = o; } }
;             __builtin_amdgcn_sched_barrier(0);
	v_lshlrev_b32_e32 v102, 16, v68
	v_and_b32_e32 v103, 0xffff0000, v68
	v_lshlrev_b32_e32 v68, 16, v69
	v_and_b32_e32 v69, 0xffff0000, v69
	v_lshlrev_b32_e32 v104, 16, v70
	v_and_b32_e32 v105, 0xffff0000, v70
	v_lshlrev_b32_e32 v70, 16, v71
	v_and_b32_e32 v71, 0xffff0000, v71
	v_lshlrev_b32_e32 v116, 16, v82
	v_and_b32_e32 v117, 0xffff0000, v82
	v_lshlrev_b32_e32 v118, 16, v64
	v_and_b32_e32 v119, 0xffff0000, v64
	v_lshlrev_b32_e32 v64, 16, v65
	v_and_b32_e32 v65, 0xffff0000, v65
	v_lshlrev_b32_e32 v106, 16, v72
	v_and_b32_e32 v107, 0xffff0000, v72
	v_lshlrev_b32_e32 v72, 16, v73
	v_and_b32_e32 v73, 0xffff0000, v73
	v_lshlrev_b32_e32 v108, 16, v74
	v_and_b32_e32 v109, 0xffff0000, v74
	v_lshlrev_b32_e32 v74, 16, v75
	v_and_b32_e32 v75, 0xffff0000, v75
	v_pk_fma_f32 v[62:63], v[68:69], s[8:9], v[62:63] op_sel_hi:[1,0,1]
	v_pk_fma_f32 v[60:61], v[102:103], s[8:9], v[60:61] op_sel_hi:[1,0,1]
	v_pk_fma_f32 v[58:59], v[70:71], s[8:9], v[58:59] op_sel_hi:[1,0,1]
	v_pk_fma_f32 v[56:57], v[104:105], s[8:9], v[56:57] op_sel_hi:[1,0,1]
	v_pk_fma_f32 v[68:69], v[116:117], s[8:9], v[32:33] op_sel_hi:[1,0,1]
	v_pk_fma_f32 v[64:65], v[64:65], s[8:9], v[30:31] op_sel_hi:[1,0,1]
	v_cvt_pk_bf16_f32 v30, v60, v61
	v_cvt_pk_bf16_f32 v31, v62, v63
	v_cvt_pk_bf16_f32 v32, v56, v57
	v_cvt_pk_bf16_f32 v33, v58, v59
	v_lshlrev_b32_e32 v110, 16, v76
	v_and_b32_e32 v111, 0xffff0000, v76
	v_lshlrev_b32_e32 v76, 16, v77
	v_and_b32_e32 v77, 0xffff0000, v77
	v_lshlrev_b32_e32 v112, 16, v78
	v_and_b32_e32 v113, 0xffff0000, v78
	v_lshlrev_b32_e32 v78, 16, v79
	v_and_b32_e32 v79, 0xffff0000, v79
	v_pk_fma_f32 v[46:47], v[72:73], s[8:9], v[46:47] op_sel_hi:[1,0,1]
	v_pk_fma_f32 v[44:45], v[106:107], s[8:9], v[44:45] op_sel_hi:[1,0,1]
	v_pk_fma_f32 v[42:43], v[74:75], s[8:9], v[42:43] op_sel_hi:[1,0,1]
	v_pk_fma_f32 v[40:41], v[108:109], s[8:9], v[40:41] op_sel_hi:[1,0,1]
	global_store_dwordx4 v[96:97], v[30:33], off sc1
	v_lshlrev_b32_e32 v114, 16, v80
	v_and_b32_e32 v115, 0xffff0000, v80
	v_cvt_pk_bf16_f32 v30, v44, v45
	v_cvt_pk_bf16_f32 v31, v46, v47
	v_cvt_pk_bf16_f32 v32, v40, v41
	v_cvt_pk_bf16_f32 v33, v42, v43
	v_lshlrev_b32_e32 v80, 16, v81
	v_and_b32_e32 v81, 0xffff0000, v81
	v_lshlrev_b32_e32 v82, 16, v83
	v_and_b32_e32 v83, 0xffff0000, v83
	v_pk_fma_f32 v[54:55], v[76:77], s[8:9], v[54:55] op_sel_hi:[1,0,1]
	v_pk_fma_f32 v[52:53], v[110:111], s[8:9], v[52:53] op_sel_hi:[1,0,1]
	v_pk_fma_f32 v[50:51], v[78:79], s[8:9], v[50:51] op_sel_hi:[1,0,1]
	v_pk_fma_f32 v[48:49], v[112:113], s[8:9], v[48:49] op_sel_hi:[1,0,1]
	global_store_dwordx4 v[96:97], v[30:33], off offset:256 sc1
	v_pk_fma_f32 v[38:39], v[80:81], s[8:9], v[38:39] op_sel_hi:[1,0,1]
	v_pk_fma_f32 v[36:37], v[114:115], s[8:9], v[36:37] op_sel_hi:[1,0,1]
	v_cvt_pk_bf16_f32 v30, v52, v53
	v_cvt_pk_bf16_f32 v31, v54, v55
	v_cvt_pk_bf16_f32 v32, v48, v49
	v_cvt_pk_bf16_f32 v33, v50, v51
	v_pk_fma_f32 v[34:35], v[82:83], s[8:9], v[34:35] op_sel_hi:[1,0,1]
	global_store_dwordx4 v[98:99], v[30:33], off sc1
	v_pk_fma_f32 v[28:29], v[118:119], s[8:9], v[28:29] op_sel_hi:[1,0,1]
	s_nop 0
	v_cvt_pk_bf16_f32 v30, v36, v37
	v_cvt_pk_bf16_f32 v31, v38, v39
	v_cvt_pk_bf16_f32 v32, v68, v69
	v_cvt_pk_bf16_f32 v33, v34, v35
	global_store_dwordx4 v[98:99], v[30:33], off offset:256 sc1
	s_nop 1
	v_lshlrev_b32_e32 v30, 16, v66
	v_and_b32_e32 v31, 0xffff0000, v66
	v_lshlrev_b32_e32 v32, 16, v67
	v_and_b32_e32 v33, 0xffff0000, v67
	v_pk_fma_f32 v[32:33], v[32:33], s[8:9], v[26:27] op_sel_hi:[1,0,1]
	v_pk_fma_f32 v[26:27], v[30:31], s[8:9], v[24:25] op_sel_hi:[1,0,1]
	v_cvt_pk_bf16_f32 v24, v28, v29
	v_cvt_pk_bf16_f32 v25, v64, v65
	s_nop 0
	v_cvt_pk_bf16_f32 v26, v26, v27
	v_cvt_pk_bf16_f32 v27, v32, v33
	global_store_dwordx4 v[100:101], v[24:27], off sc1
	s_nop 1
	v_lshlrev_b32_e32 v24, 16, v84
	v_and_b32_e32 v25, 0xffff0000, v84
	v_lshlrev_b32_e32 v26, 16, v85
	v_and_b32_e32 v27, 0xffff0000, v85
	v_pk_fma_f32 v[22:23], v[26:27], s[8:9], v[22:23] op_sel_hi:[1,0,1]
	v_pk_fma_f32 v[20:21], v[24:25], s[8:9], v[20:21] op_sel_hi:[1,0,1]
	v_lshlrev_b32_e32 v24, 16, v86
	v_and_b32_e32 v25, 0xffff0000, v86
	v_lshlrev_b32_e32 v26, 16, v87
	v_and_b32_e32 v27, 0xffff0000, v87
	v_pk_fma_f32 v[26:27], v[26:27], s[8:9], v[18:19] op_sel_hi:[1,0,1]
	v_pk_fma_f32 v[18:19], v[24:25], s[8:9], v[16:17] op_sel_hi:[1,0,1]
	v_cvt_pk_bf16_f32 v16, v20, v21
	v_cvt_pk_bf16_f32 v17, v22, v23
	v_lshlrev_b32_e32 v20, 16, v89
	v_cvt_pk_bf16_f32 v18, v18, v19
	v_cvt_pk_bf16_f32 v19, v26, v27
	global_store_dwordx4 v[100:101], v[16:19], off offset:256 sc1
	v_and_b32_e32 v21, 0xffff0000, v89
	v_pk_fma_f32 v[14:15], v[20:21], s[8:9], v[14:15] op_sel_hi:[1,0,1]
	v_lshlrev_b32_e32 v18, 16, v88
	v_and_b32_e32 v19, 0xffff0000, v88
	v_pk_fma_f32 v[12:13], v[18:19], s[8:9], v[12:13] op_sel_hi:[1,0,1]
	v_lshlrev_b32_e32 v18, 16, v90
	v_and_b32_e32 v19, 0xffff0000, v90
	v_lshlrev_b32_e32 v20, 16, v91
	v_and_b32_e32 v21, 0xffff0000, v91
	v_pk_fma_f32 v[20:21], v[20:21], s[8:9], v[10:11] op_sel_hi:[1,0,1]
	v_pk_fma_f32 v[10:11], v[18:19], s[8:9], v[8:9] op_sel_hi:[1,0,1]
	v_lshl_add_u64 v[16:17], v[172:173], 0, v[174:175]
	v_cvt_pk_bf16_f32 v8, v12, v13
	v_cvt_pk_bf16_f32 v9, v14, v15
	v_cvt_pk_bf16_f32 v10, v10, v11
	v_cvt_pk_bf16_f32 v11, v20, v21
	global_store_dwordx4 v[16:17], v[8:11], off sc1
	s_nop 1
	v_lshlrev_b32_e32 v8, 16, v92
	v_and_b32_e32 v9, 0xffff0000, v92
	v_lshlrev_b32_e32 v10, 16, v93
	v_and_b32_e32 v11, 0xffff0000, v93
	v_pk_fma_f32 v[6:7], v[10:11], s[8:9], v[6:7] op_sel_hi:[1,0,1]
	v_pk_fma_f32 v[4:5], v[8:9], s[8:9], v[4:5] op_sel_hi:[1,0,1]
	v_lshlrev_b32_e32 v8, 16, v94
	v_and_b32_e32 v9, 0xffff0000, v94
	v_lshlrev_b32_e32 v10, 16, v95
	v_and_b32_e32 v11, 0xffff0000, v95
	v_pk_fma_f32 v[10:11], v[10:11], s[8:9], v[2:3] op_sel_hi:[1,0,1]
	v_pk_fma_f32 v[2:3], v[8:9], s[8:9], v[0:1] op_sel_hi:[1,0,1]
	v_cvt_pk_bf16_f32 v0, v4, v5
	v_cvt_pk_bf16_f32 v1, v6, v7
	s_nop 0
	v_cvt_pk_bf16_f32 v2, v2, v3
	v_cvt_pk_bf16_f32 v3, v10, v11
	global_store_dwordx4 v[16:17], v[0:3], off offset:256 sc1
	s_cmp_eq_u32 s37, 4
	s_mov_b32 s38, s37
	s_mov_b64 s[12:13], s[10:11]
	s_cbranch_scc0 .LBB0_554
	s_waitcnt vmcnt(0)
	s_cmpk_gt_u32 s9, 0xff
	s_cbranch_scc1 .LBB0_559
	s_barrier
